# v93: v91 + in-projection RoPE epilogue: table loads of the next row group issued before the current group's arithmetic/stores (second 16-register buffer)
# baseline (speedup 1.0000x reference)
; __device__ __forceinline__ u32x4 pack8(const f32x4& a, const f32x4& b) { u32x4 w; w.x = cvt_pk_bf16(a[0], a[1]); w.y = cvt_pk_bf16(a[2], a[3]); w.z = cvt_pk_bf16(b[0], b[1]); w.w = cvt_pk_bf16(b[2], b[3]); return w; }
;     __device__ __forceinline__ void operator()(const f32x4 (&acc)[2][2][4][2], const Unit& u, int wr, int wc, int fr, int fq) const {
;     ...
;             float sc; int i0, d1, dd, tp; const float *ct, *st;
;             if (type == 1) { sc = pn < 4 ? SC_A : 1.f; i0 = 8 * fq; d1 = pn * BM + 64 * wc + i0; dd = 32; tp = 32; ct = cosA; st = sinA; }
;             else { const bool isq = (pn < 16) || (pn == 16 && wc < 2); sc = isq ? SC_B : 1.f; i0 = 32 * (wc & 1) + 8 * fq; d1 = pn * BM + 128 * (wc >> 1) + i0; dd = 64; tp = 64; ct = cosB; st = sinB; }
; #pragma unroll
;             for (int ai = 0; ai < 2; ++ai)
; #pragma unroll
;                 for (int m = 0; m < 4; ++m) { const int row = row0 + ai * HALF + m * 16, pos = row & (SEQ - 1); const float scr = sc * rs[ai][m];
;                     const f32x4 c0 = *(const f32x4*)(ct + pos * tp + i0), c1 = *(const f32x4*)(ct + pos * tp + i0 + 4), s0 = *(const f32x4*)(st + pos * tp + i0), s1 = *(const f32x4*)(st + pos * tp + i0 + 4);
;                     const f32x4 x10 = acc[ai][0][m][0], x11 = acc[ai][0][m][1], x20 = acc[ai][1][m][0], x21 = acc[ai][1][m][1];
;                     const f32x4 a0 = (x10 * c0 - x20 * s0) * scr, a1 = (x11 * c1 - x21 * s1) * scr, b0 = (x10 * s0 + x20 * c0) * scr, b1 = (x11 * s1 + x21 * c1) * scr;
;                     bf16_t* rowp = O + (size_t)row * LDP + d1;
;                     *(u32x4*)(rowp) = pack8(a0, a1); *(u32x4*)(rowp + dd) = pack8(b0, b1); }
.LBB0_295:
	s_add_u32 s8, s14, s8
	s_addc_u32 s9, s15, s9
	s_add_u32 s6, s14, s6
	v_lshlrev_b32_e32 v178, 2, v130
	v_and_b32_e32 v130, 0xfcf, v154
	s_addc_u32 s7, s15, s7
	v_mul_u32_u24_e32 v130, s0, v130
	v_lshl_add_u64 v[172:173], s[6:7], 0, v[178:179]
	v_lshl_add_u64 v[188:189], s[8:9], 0, v[178:179]
	v_lshlrev_b32_e32 v178, 2, v130
	v_lshl_add_u64 v[130:131], v[188:189], 0, v[178:179]
	global_load_dwordx4 v[142:145], v[130:131], off
	global_load_dwordx4 v[138:141], v[130:131], off offset:16
	v_lshl_add_u64 v[130:131], v[172:173], 0, v[178:179]
	global_load_dwordx4 v[134:137], v[130:131], off
	s_nop 0
	global_load_dwordx4 v[130:133], v[130:131], off offset:16
	v_lshl_or_b32 v176, s53, 8, v174
	v_mul_f32_e32 v190, v158, v222
	v_mov_b64_e32 v[174:175], s[18:19]
	v_and_b32_e32 v178, 0xfdf, v191
	v_ashrrev_i32_e32 v177, 31, v176
	v_mad_i64_i32 v[194:195], s[6:7], v154, s33, v[174:175]
	v_mul_u32_u24_e32 v178, s0, v178
	v_lshlrev_b64 v[176:177], 1, v[176:177]
	v_lshl_add_u64 v[194:195], v[194:195], 0, v[176:177]
	s_lshl_b32 s58, s0, 1
	v_lshlrev_b32_e32 v178, 2, v178
	v_lshl_add_u64 v[206:207], v[194:195], 0, s[58:59]
	v_lshl_add_u64 v[208:209], v[188:189], 0, v[178:179]
	global_load_dwordx4 v[232:235], v[208:209], off
	s_nop 0
	global_load_dwordx4 v[236:239], v[208:209], off offset:16
	v_lshl_add_u64 v[248:249], v[172:173], 0, v[178:179]
	global_load_dwordx4 v[240:243], v[248:249], off
	s_nop 0
	global_load_dwordx4 v[244:247], v[248:249], off offset:16
	s_waitcnt vmcnt(7)
	v_pk_mul_f32 v[210:211], v[116:117], v[144:145]
	v_pk_mul_f32 v[212:213], v[114:115], v[142:143]
	s_waitcnt vmcnt(6)
	v_pk_mul_f32 v[224:225], v[108:109], v[140:141]
	v_pk_mul_f32 v[226:227], v[106:107], v[138:139]
	v_pk_mul_f32 v[144:145], v[128:129], v[144:145]
	v_pk_mul_f32 v[142:143], v[126:127], v[142:143]
	v_pk_mul_f32 v[140:141], v[124:125], v[140:141]
	v_pk_mul_f32 v[138:139], v[122:123], v[138:139]
	s_waitcnt vmcnt(5)
	v_pk_fma_f32 v[210:211], v[128:129], v[136:137], v[210:211] neg_lo:[0,0,1] neg_hi:[0,0,1]
	v_pk_fma_f32 v[212:213], v[126:127], v[134:135], v[212:213] neg_lo:[0,0,1] neg_hi:[0,0,1]
	s_waitcnt vmcnt(4)
	v_pk_fma_f32 v[224:225], v[124:125], v[132:133], v[224:225] neg_lo:[0,0,1] neg_hi:[0,0,1]
	v_pk_fma_f32 v[226:227], v[122:123], v[130:131], v[226:227] neg_lo:[0,0,1] neg_hi:[0,0,1]
	v_pk_fma_f32 v[136:137], v[116:117], v[136:137], v[144:145]
	v_pk_fma_f32 v[134:135], v[114:115], v[134:135], v[142:143]
	v_pk_fma_f32 v[132:133], v[108:109], v[132:133], v[140:141]
	v_pk_fma_f32 v[130:131], v[106:107], v[130:131], v[138:139]
	v_pk_mul_f32 v[138:139], v[190:191], v[210:211] op_sel_hi:[0,1]
	v_pk_mul_f32 v[140:141], v[190:191], v[212:213] op_sel_hi:[0,1]
	v_pk_mul_f32 v[142:143], v[190:191], v[224:225] op_sel_hi:[0,1]
	v_pk_mul_f32 v[144:145], v[190:191], v[226:227] op_sel_hi:[0,1]
	v_pk_mul_f32 v[136:137], v[190:191], v[136:137] op_sel_hi:[0,1]
	v_pk_mul_f32 v[134:135], v[190:191], v[134:135] op_sel_hi:[0,1]
	v_pk_mul_f32 v[210:211], v[190:191], v[132:133] op_sel_hi:[0,1]
	v_pk_mul_f32 v[212:213], v[190:191], v[130:131] op_sel_hi:[0,1]
	v_cvt_pk_bf16_f32 v130, v140, v141
	v_cvt_pk_bf16_f32 v131, v138, v139
	v_cvt_pk_bf16_f32 v132, v144, v145
	v_cvt_pk_bf16_f32 v133, v142, v143
	v_cvt_pk_bf16_f32 v134, v134, v135
	v_cvt_pk_bf16_f32 v135, v136, v137
	v_cvt_pk_bf16_f32 v136, v212, v213
	v_cvt_pk_bf16_f32 v137, v210, v211
	global_store_dwordx4 v[194:195], v[130:133], off
	global_store_dwordx4 v[206:207], v[134:137], off
	v_mul_f32_e32 v190, v156, v222
	v_and_b32_e32 v178, 0xfef, v155
	v_mad_i64_i32 v[194:195], s[6:7], v191, s33, v[174:175]
	v_mul_u32_u24_e32 v178, s0, v178
	v_lshl_add_u64 v[194:195], v[194:195], 0, v[176:177]
	v_lshlrev_b32_e32 v178, 2, v178
	v_lshl_add_u64 v[206:207], v[194:195], 0, s[58:59]
	v_lshl_add_u64 v[208:209], v[188:189], 0, v[178:179]
	global_load_dwordx4 v[130:133], v[208:209], off
	s_nop 0
	global_load_dwordx4 v[134:137], v[208:209], off offset:16
	v_lshl_add_u64 v[248:249], v[172:173], 0, v[178:179]
	global_load_dwordx4 v[138:141], v[248:249], off
	s_nop 0
	global_load_dwordx4 v[142:145], v[248:249], off offset:16
	s_waitcnt vmcnt(7)
	v_pk_mul_f32 v[210:211], v[100:101], v[234:235]
	v_pk_mul_f32 v[212:213], v[98:99], v[232:233]
	s_waitcnt vmcnt(6)
	v_pk_mul_f32 v[224:225], v[92:93], v[238:239]
	v_pk_mul_f32 v[226:227], v[90:91], v[236:237]
	v_pk_mul_f32 v[234:235], v[120:121], v[234:235]
	v_pk_mul_f32 v[232:233], v[118:119], v[232:233]
	v_pk_mul_f32 v[238:239], v[112:113], v[238:239]
	v_pk_mul_f32 v[236:237], v[110:111], v[236:237]
	s_waitcnt vmcnt(5)
	v_pk_fma_f32 v[210:211], v[120:121], v[242:243], v[210:211] neg_lo:[0,0,1] neg_hi:[0,0,1]
	v_pk_fma_f32 v[212:213], v[118:119], v[240:241], v[212:213] neg_lo:[0,0,1] neg_hi:[0,0,1]
	s_waitcnt vmcnt(4)
; __device__ __forceinline__ u32x4 pack8(const f32x4& a, const f32x4& b) { u32x4 w; w.x = cvt_pk_bf16(a[0], a[1]); w.y = cvt_pk_bf16(a[2], a[3]); w.z = cvt_pk_bf16(b[0], b[1]); w.w = cvt_pk_bf16(b[2], b[3]); return w; }
;     __device__ __forceinline__ void operator()(const f32x4 (&acc)[2][2][4][2], const Unit& u, int wr, int wc, int fr, int fq) const {
;     ...
;                 for (int m = 0; m < 4; ++m) { const int row = row0 + ai * HALF + m * 16, pos = row & (SEQ - 1); const float scr = sc * rs[ai][m];
;                     const f32x4 c0 = *(const f32x4*)(ct + pos * tp + i0), c1 = *(const f32x4*)(ct + pos * tp + i0 + 4), s0 = *(const f32x4*)(st + pos * tp + i0), s1 = *(const f32x4*)(st + pos * tp + i0 + 4);
;                     const f32x4 x10 = acc[ai][0][m][0], x11 = acc[ai][0][m][1], x20 = acc[ai][1][m][0], x21 = acc[ai][1][m][1];
;                     const f32x4 a0 = (x10 * c0 - x20 * s0) * scr, a1 = (x11 * c1 - x21 * s1) * scr, b0 = (x10 * s0 + x20 * c0) * scr, b1 = (x11 * s1 + x21 * c1) * scr;
;                     bf16_t* rowp = O + (size_t)row * LDP + d1;
;                     *(u32x4*)(rowp) = pack8(a0, a1); *(u32x4*)(rowp + dd) = pack8(b0, b1); }
	v_pk_fma_f32 v[224:225], v[112:113], v[246:247], v[224:225] neg_lo:[0,0,1] neg_hi:[0,0,1]
	v_pk_fma_f32 v[226:227], v[110:111], v[244:245], v[226:227] neg_lo:[0,0,1] neg_hi:[0,0,1]
	v_pk_fma_f32 v[234:235], v[100:101], v[242:243], v[234:235]
	v_pk_fma_f32 v[232:233], v[98:99], v[240:241], v[232:233]
	v_pk_fma_f32 v[238:239], v[92:93], v[246:247], v[238:239]
	v_pk_fma_f32 v[236:237], v[90:91], v[244:245], v[236:237]
	v_pk_mul_f32 v[240:241], v[190:191], v[210:211] op_sel_hi:[0,1]
	v_pk_mul_f32 v[242:243], v[190:191], v[212:213] op_sel_hi:[0,1]
	v_pk_mul_f32 v[244:245], v[190:191], v[224:225] op_sel_hi:[0,1]
	v_pk_mul_f32 v[246:247], v[190:191], v[226:227] op_sel_hi:[0,1]
	v_pk_mul_f32 v[210:211], v[190:191], v[234:235] op_sel_hi:[0,1]
	v_pk_mul_f32 v[212:213], v[190:191], v[232:233] op_sel_hi:[0,1]
	v_pk_mul_f32 v[224:225], v[190:191], v[238:239] op_sel_hi:[0,1]
	v_pk_mul_f32 v[238:239], v[190:191], v[236:237] op_sel_hi:[0,1]
	v_cvt_pk_bf16_f32 v232, v242, v243
	v_cvt_pk_bf16_f32 v233, v240, v241
	v_cvt_pk_bf16_f32 v234, v246, v247
	v_cvt_pk_bf16_f32 v235, v244, v245
	v_cvt_pk_bf16_f32 v236, v212, v213
	v_cvt_pk_bf16_f32 v237, v210, v211
	v_cvt_pk_bf16_f32 v238, v238, v239
	v_cvt_pk_bf16_f32 v239, v224, v225
	global_store_dwordx4 v[194:195], v[232:235], off
	global_store_dwordx4 v[206:207], v[236:239], off
	v_mul_f32_e32 v190, v160, v222
	v_and_b32_e32 v178, 0xfff, v217
	v_mad_i64_i32 v[194:195], s[6:7], v155, s33, v[174:175]
	v_mul_u32_u24_e32 v178, s0, v178
	v_lshl_add_u64 v[194:195], v[194:195], 0, v[176:177]
	v_lshlrev_b32_e32 v178, 2, v178
	v_lshl_add_u64 v[206:207], v[194:195], 0, s[58:59]
	v_lshl_add_u64 v[208:209], v[188:189], 0, v[178:179]
	global_load_dwordx4 v[232:235], v[208:209], off
	s_nop 0
	global_load_dwordx4 v[236:239], v[208:209], off offset:16
	v_lshl_add_u64 v[248:249], v[172:173], 0, v[178:179]
	global_load_dwordx4 v[240:243], v[248:249], off
	s_nop 0
	global_load_dwordx4 v[244:247], v[248:249], off offset:16
	s_waitcnt vmcnt(7)
	v_pk_mul_f32 v[210:211], v[84:85], v[132:133]
	v_pk_mul_f32 v[212:213], v[82:83], v[130:131]
	s_waitcnt vmcnt(6)
	v_pk_mul_f32 v[224:225], v[76:77], v[136:137]
	v_pk_mul_f32 v[226:227], v[74:75], v[134:135]
	v_pk_mul_f32 v[132:133], v[104:105], v[132:133]
	v_pk_mul_f32 v[130:131], v[102:103], v[130:131]
	v_pk_mul_f32 v[136:137], v[96:97], v[136:137]
	v_pk_mul_f32 v[134:135], v[94:95], v[134:135]
	s_waitcnt vmcnt(5)
	v_pk_fma_f32 v[210:211], v[104:105], v[140:141], v[210:211] neg_lo:[0,0,1] neg_hi:[0,0,1]
	v_pk_fma_f32 v[212:213], v[102:103], v[138:139], v[212:213] neg_lo:[0,0,1] neg_hi:[0,0,1]
	s_waitcnt vmcnt(4)
	v_pk_fma_f32 v[224:225], v[96:97], v[144:145], v[224:225] neg_lo:[0,0,1] neg_hi:[0,0,1]
	v_pk_fma_f32 v[226:227], v[94:95], v[142:143], v[226:227] neg_lo:[0,0,1] neg_hi:[0,0,1]
	v_pk_fma_f32 v[132:133], v[84:85], v[140:141], v[132:133]
	v_pk_fma_f32 v[130:131], v[82:83], v[138:139], v[130:131]
	v_pk_fma_f32 v[136:137], v[76:77], v[144:145], v[136:137]
	v_pk_fma_f32 v[134:135], v[74:75], v[142:143], v[134:135]
	v_pk_mul_f32 v[138:139], v[190:191], v[210:211] op_sel_hi:[0,1]
	v_pk_mul_f32 v[140:141], v[190:191], v[212:213] op_sel_hi:[0,1]
	v_pk_mul_f32 v[142:143], v[190:191], v[224:225] op_sel_hi:[0,1]
	v_pk_mul_f32 v[144:145], v[190:191], v[226:227] op_sel_hi:[0,1]
	v_pk_mul_f32 v[210:211], v[190:191], v[132:133] op_sel_hi:[0,1]
	v_pk_mul_f32 v[212:213], v[190:191], v[130:131] op_sel_hi:[0,1]
	v_pk_mul_f32 v[224:225], v[190:191], v[136:137] op_sel_hi:[0,1]
	v_pk_mul_f32 v[136:137], v[190:191], v[134:135] op_sel_hi:[0,1]
	v_cvt_pk_bf16_f32 v130, v140, v141
	v_cvt_pk_bf16_f32 v131, v138, v139
	v_cvt_pk_bf16_f32 v132, v144, v145
	v_cvt_pk_bf16_f32 v133, v142, v143
	v_cvt_pk_bf16_f32 v134, v212, v213
	v_cvt_pk_bf16_f32 v135, v210, v211
	v_cvt_pk_bf16_f32 v136, v136, v137
	v_cvt_pk_bf16_f32 v137, v224, v225
	global_store_dwordx4 v[194:195], v[130:133], off
	global_store_dwordx4 v[206:207], v[134:137], off
	v_mul_f32_e32 v190, v162, v222
	v_and_b32_e32 v178, 0xfcf, v218
	v_mad_i64_i32 v[194:195], s[6:7], v217, s33, v[174:175]
	v_mul_u32_u24_e32 v178, s0, v178
	v_lshl_add_u64 v[194:195], v[194:195], 0, v[176:177]
	v_lshlrev_b32_e32 v178, 2, v178
	v_lshl_add_u64 v[206:207], v[194:195], 0, s[58:59]
	v_lshl_add_u64 v[208:209], v[188:189], 0, v[178:179]
	global_load_dwordx4 v[130:133], v[208:209], off
	s_nop 0
	global_load_dwordx4 v[134:137], v[208:209], off offset:16
	v_lshl_add_u64 v[248:249], v[172:173], 0, v[178:179]
	global_load_dwordx4 v[138:141], v[248:249], off
	s_nop 0
	global_load_dwordx4 v[142:145], v[248:249], off offset:16
	s_waitcnt vmcnt(7)
	v_pk_mul_f32 v[210:211], v[72:73], v[234:235]
	v_pk_mul_f32 v[212:213], v[70:71], v[232:233]
	s_waitcnt vmcnt(6)
	v_pk_mul_f32 v[224:225], v[68:69], v[238:239]
	v_pk_mul_f32 v[226:227], v[66:67], v[236:237]
	v_pk_mul_f32 v[234:235], v[88:89], v[234:235]
	v_pk_mul_f32 v[232:233], v[86:87], v[232:233]
	v_pk_mul_f32 v[238:239], v[80:81], v[238:239]
	v_pk_mul_f32 v[236:237], v[78:79], v[236:237]
	s_waitcnt vmcnt(5)
	v_pk_fma_f32 v[210:211], v[88:89], v[242:243], v[210:211] neg_lo:[0,0,1] neg_hi:[0,0,1]
	v_pk_fma_f32 v[212:213], v[86:87], v[240:241], v[212:213] neg_lo:[0,0,1] neg_hi:[0,0,1]
	s_waitcnt vmcnt(4)
; __device__ __forceinline__ u32x4 pack8(const f32x4& a, const f32x4& b) { u32x4 w; w.x = cvt_pk_bf16(a[0], a[1]); w.y = cvt_pk_bf16(a[2], a[3]); w.z = cvt_pk_bf16(b[0], b[1]); w.w = cvt_pk_bf16(b[2], b[3]); return w; }
;     __device__ __forceinline__ void operator()(const f32x4 (&acc)[2][2][4][2], const Unit& u, int wr, int wc, int fr, int fq) const {
;     ...
;                 for (int m = 0; m < 4; ++m) { const int row = row0 + ai * HALF + m * 16, pos = row & (SEQ - 1); const float scr = sc * rs[ai][m];
;                     const f32x4 c0 = *(const f32x4*)(ct + pos * tp + i0), c1 = *(const f32x4*)(ct + pos * tp + i0 + 4), s0 = *(const f32x4*)(st + pos * tp + i0), s1 = *(const f32x4*)(st + pos * tp + i0 + 4);
;                     const f32x4 x10 = acc[ai][0][m][0], x11 = acc[ai][0][m][1], x20 = acc[ai][1][m][0], x21 = acc[ai][1][m][1];
;                     const f32x4 a0 = (x10 * c0 - x20 * s0) * scr, a1 = (x11 * c1 - x21 * s1) * scr, b0 = (x10 * s0 + x20 * c0) * scr, b1 = (x11 * s1 + x21 * c1) * scr;
;                     bf16_t* rowp = O + (size_t)row * LDP + d1;
;                     *(u32x4*)(rowp) = pack8(a0, a1); *(u32x4*)(rowp + dd) = pack8(b0, b1); }
	v_pk_fma_f32 v[224:225], v[80:81], v[246:247], v[224:225] neg_lo:[0,0,1] neg_hi:[0,0,1]
	v_pk_fma_f32 v[226:227], v[78:79], v[244:245], v[226:227] neg_lo:[0,0,1] neg_hi:[0,0,1]
	v_pk_fma_f32 v[234:235], v[72:73], v[242:243], v[234:235]
	v_pk_fma_f32 v[232:233], v[70:71], v[240:241], v[232:233]
	v_pk_fma_f32 v[238:239], v[68:69], v[246:247], v[238:239]
	v_pk_fma_f32 v[236:237], v[66:67], v[244:245], v[236:237]
	v_pk_mul_f32 v[240:241], v[190:191], v[210:211] op_sel_hi:[0,1]
	v_pk_mul_f32 v[242:243], v[190:191], v[212:213] op_sel_hi:[0,1]
	v_pk_mul_f32 v[244:245], v[190:191], v[224:225] op_sel_hi:[0,1]
	v_pk_mul_f32 v[246:247], v[190:191], v[226:227] op_sel_hi:[0,1]
	v_pk_mul_f32 v[210:211], v[190:191], v[234:235] op_sel_hi:[0,1]
	v_pk_mul_f32 v[212:213], v[190:191], v[232:233] op_sel_hi:[0,1]
	v_pk_mul_f32 v[224:225], v[190:191], v[238:239] op_sel_hi:[0,1]
	v_pk_mul_f32 v[238:239], v[190:191], v[236:237] op_sel_hi:[0,1]
	v_cvt_pk_bf16_f32 v232, v242, v243
	v_cvt_pk_bf16_f32 v233, v240, v241
	v_cvt_pk_bf16_f32 v234, v246, v247
	v_cvt_pk_bf16_f32 v235, v244, v245
	v_cvt_pk_bf16_f32 v236, v212, v213
	v_cvt_pk_bf16_f32 v237, v210, v211
	v_cvt_pk_bf16_f32 v238, v238, v239
	v_cvt_pk_bf16_f32 v239, v224, v225
	global_store_dwordx4 v[194:195], v[232:235], off
	global_store_dwordx4 v[206:207], v[236:239], off
	v_mul_f32_e32 v190, v164, v222
	v_and_b32_e32 v178, 0xfdf, v219
	v_mad_i64_i32 v[194:195], s[6:7], v218, s33, v[174:175]
	v_mul_u32_u24_e32 v178, s0, v178
	v_lshl_add_u64 v[194:195], v[194:195], 0, v[176:177]
	v_lshlrev_b32_e32 v178, 2, v178
	v_lshl_add_u64 v[206:207], v[194:195], 0, s[58:59]
	v_lshl_add_u64 v[208:209], v[188:189], 0, v[178:179]
	global_load_dwordx4 v[232:235], v[208:209], off
	s_nop 0
	global_load_dwordx4 v[236:239], v[208:209], off offset:16
	v_lshl_add_u64 v[248:249], v[172:173], 0, v[178:179]
	global_load_dwordx4 v[240:243], v[248:249], off
	s_nop 0
	global_load_dwordx4 v[244:247], v[248:249], off offset:16
	s_waitcnt vmcnt(7)
	v_pk_mul_f32 v[210:211], v[52:53], v[132:133]
	v_pk_mul_f32 v[212:213], v[50:51], v[130:131]
	s_waitcnt vmcnt(6)
	v_pk_mul_f32 v[224:225], v[44:45], v[136:137]
	v_pk_mul_f32 v[226:227], v[42:43], v[134:135]
	v_pk_mul_f32 v[132:133], v[64:65], v[132:133]
	v_pk_mul_f32 v[130:131], v[62:63], v[130:131]
	v_pk_mul_f32 v[136:137], v[60:61], v[136:137]
	v_pk_mul_f32 v[134:135], v[58:59], v[134:135]
	s_waitcnt vmcnt(5)
	v_pk_fma_f32 v[210:211], v[64:65], v[140:141], v[210:211] neg_lo:[0,0,1] neg_hi:[0,0,1]
	v_pk_fma_f32 v[212:213], v[62:63], v[138:139], v[212:213] neg_lo:[0,0,1] neg_hi:[0,0,1]
	s_waitcnt vmcnt(4)
	v_pk_fma_f32 v[224:225], v[60:61], v[144:145], v[224:225] neg_lo:[0,0,1] neg_hi:[0,0,1]
	v_pk_fma_f32 v[226:227], v[58:59], v[142:143], v[226:227] neg_lo:[0,0,1] neg_hi:[0,0,1]
	v_pk_fma_f32 v[132:133], v[52:53], v[140:141], v[132:133]
	v_pk_fma_f32 v[130:131], v[50:51], v[138:139], v[130:131]
	v_pk_fma_f32 v[136:137], v[44:45], v[144:145], v[136:137]
	v_pk_fma_f32 v[134:135], v[42:43], v[142:143], v[134:135]
	v_pk_mul_f32 v[138:139], v[190:191], v[210:211] op_sel_hi:[0,1]
	v_pk_mul_f32 v[140:141], v[190:191], v[212:213] op_sel_hi:[0,1]
	v_pk_mul_f32 v[142:143], v[190:191], v[224:225] op_sel_hi:[0,1]
	v_pk_mul_f32 v[144:145], v[190:191], v[226:227] op_sel_hi:[0,1]
	v_pk_mul_f32 v[210:211], v[190:191], v[132:133] op_sel_hi:[0,1]
	v_pk_mul_f32 v[212:213], v[190:191], v[130:131] op_sel_hi:[0,1]
	v_pk_mul_f32 v[224:225], v[190:191], v[136:137] op_sel_hi:[0,1]
	v_pk_mul_f32 v[136:137], v[190:191], v[134:135] op_sel_hi:[0,1]
	v_cvt_pk_bf16_f32 v130, v140, v141
	v_cvt_pk_bf16_f32 v131, v138, v139
	v_cvt_pk_bf16_f32 v132, v144, v145
	v_cvt_pk_bf16_f32 v133, v142, v143
	v_cvt_pk_bf16_f32 v134, v212, v213
	v_cvt_pk_bf16_f32 v135, v210, v211
	v_cvt_pk_bf16_f32 v136, v136, v137
	v_cvt_pk_bf16_f32 v137, v224, v225
	global_store_dwordx4 v[194:195], v[130:133], off
	global_store_dwordx4 v[206:207], v[134:137], off
	v_mul_f32_e32 v190, v166, v222
	v_and_b32_e32 v178, 0xfef, v220
	v_mad_i64_i32 v[194:195], s[6:7], v219, s33, v[174:175]
	v_mul_u32_u24_e32 v178, s0, v178
	v_lshl_add_u64 v[194:195], v[194:195], 0, v[176:177]
	v_lshlrev_b32_e32 v178, 2, v178
	v_lshl_add_u64 v[206:207], v[194:195], 0, s[58:59]
	v_lshl_add_u64 v[208:209], v[188:189], 0, v[178:179]
	global_load_dwordx4 v[130:133], v[208:209], off
	s_nop 0
	global_load_dwordx4 v[134:137], v[208:209], off offset:16
	v_lshl_add_u64 v[248:249], v[172:173], 0, v[178:179]
	global_load_dwordx4 v[138:141], v[248:249], off
	s_nop 0
	global_load_dwordx4 v[142:145], v[248:249], off offset:16
	s_waitcnt vmcnt(7)
	v_pk_mul_f32 v[210:211], v[36:37], v[234:235]
	v_pk_mul_f32 v[212:213], v[34:35], v[232:233]
	s_waitcnt vmcnt(6)
	v_pk_mul_f32 v[224:225], v[28:29], v[238:239]
	v_pk_mul_f32 v[226:227], v[26:27], v[236:237]
	v_pk_mul_f32 v[234:235], v[56:57], v[234:235]
	v_pk_mul_f32 v[232:233], v[54:55], v[232:233]
	v_pk_mul_f32 v[238:239], v[48:49], v[238:239]
	v_pk_mul_f32 v[236:237], v[46:47], v[236:237]
	s_waitcnt vmcnt(5)
	v_pk_fma_f32 v[210:211], v[56:57], v[242:243], v[210:211] neg_lo:[0,0,1] neg_hi:[0,0,1]
	v_pk_fma_f32 v[212:213], v[54:55], v[240:241], v[212:213] neg_lo:[0,0,1] neg_hi:[0,0,1]
	s_waitcnt vmcnt(4)
; __device__ __forceinline__ u32x4 pack8(const f32x4& a, const f32x4& b) { u32x4 w; w.x = cvt_pk_bf16(a[0], a[1]); w.y = cvt_pk_bf16(a[2], a[3]); w.z = cvt_pk_bf16(b[0], b[1]); w.w = cvt_pk_bf16(b[2], b[3]); return w; }
;     __device__ __forceinline__ void operator()(const f32x4 (&acc)[2][2][4][2], const Unit& u, int wr, int wc, int fr, int fq) const {
;     ...
;                 for (int m = 0; m < 4; ++m) { const int row = row0 + ai * HALF + m * 16, pos = row & (SEQ - 1); const float scr = sc * rs[ai][m];
;                     const f32x4 c0 = *(const f32x4*)(ct + pos * tp + i0), c1 = *(const f32x4*)(ct + pos * tp + i0 + 4), s0 = *(const f32x4*)(st + pos * tp + i0), s1 = *(const f32x4*)(st + pos * tp + i0 + 4);
;                     const f32x4 x10 = acc[ai][0][m][0], x11 = acc[ai][0][m][1], x20 = acc[ai][1][m][0], x21 = acc[ai][1][m][1];
;                     const f32x4 a0 = (x10 * c0 - x20 * s0) * scr, a1 = (x11 * c1 - x21 * s1) * scr, b0 = (x10 * s0 + x20 * c0) * scr, b1 = (x11 * s1 + x21 * c1) * scr;
;                     bf16_t* rowp = O + (size_t)row * LDP + d1;
;                     *(u32x4*)(rowp) = pack8(a0, a1); *(u32x4*)(rowp + dd) = pack8(b0, b1); }
	v_pk_fma_f32 v[224:225], v[48:49], v[246:247], v[224:225] neg_lo:[0,0,1] neg_hi:[0,0,1]
	v_pk_fma_f32 v[226:227], v[46:47], v[244:245], v[226:227] neg_lo:[0,0,1] neg_hi:[0,0,1]
	v_pk_fma_f32 v[234:235], v[36:37], v[242:243], v[234:235]
	v_pk_fma_f32 v[232:233], v[34:35], v[240:241], v[232:233]
	v_pk_fma_f32 v[238:239], v[28:29], v[246:247], v[238:239]
	v_pk_fma_f32 v[236:237], v[26:27], v[244:245], v[236:237]
	v_pk_mul_f32 v[240:241], v[190:191], v[210:211] op_sel_hi:[0,1]
	v_pk_mul_f32 v[242:243], v[190:191], v[212:213] op_sel_hi:[0,1]
	v_pk_mul_f32 v[244:245], v[190:191], v[224:225] op_sel_hi:[0,1]
	v_pk_mul_f32 v[246:247], v[190:191], v[226:227] op_sel_hi:[0,1]
	v_pk_mul_f32 v[210:211], v[190:191], v[234:235] op_sel_hi:[0,1]
	v_pk_mul_f32 v[212:213], v[190:191], v[232:233] op_sel_hi:[0,1]
	v_pk_mul_f32 v[224:225], v[190:191], v[238:239] op_sel_hi:[0,1]
	v_pk_mul_f32 v[238:239], v[190:191], v[236:237] op_sel_hi:[0,1]
	v_cvt_pk_bf16_f32 v232, v242, v243
	v_cvt_pk_bf16_f32 v233, v240, v241
	v_cvt_pk_bf16_f32 v234, v246, v247
	v_cvt_pk_bf16_f32 v235, v244, v245
	v_cvt_pk_bf16_f32 v236, v212, v213
	v_cvt_pk_bf16_f32 v237, v210, v211
	v_cvt_pk_bf16_f32 v238, v238, v239
	v_cvt_pk_bf16_f32 v239, v224, v225
	global_store_dwordx4 v[194:195], v[232:235], off
	global_store_dwordx4 v[206:207], v[236:239], off
	v_mul_f32_e32 v190, v170, v222
	v_and_b32_e32 v178, 0xfff, v221
	v_mad_i64_i32 v[194:195], s[6:7], v220, s33, v[174:175]
	v_mul_u32_u24_e32 v178, s0, v178
	v_lshl_add_u64 v[194:195], v[194:195], 0, v[176:177]
	v_lshlrev_b32_e32 v178, 2, v178
	v_lshl_add_u64 v[206:207], v[194:195], 0, s[58:59]
	v_lshl_add_u64 v[188:189], v[188:189], 0, v[178:179]
	v_mad_i64_i32 v[174:175], s[0:1], v221, s33, v[174:175]
	v_lshl_add_u64 v[174:175], v[174:175], 0, v[176:177]
	v_lshl_add_u64 v[176:177], v[174:175], 0, s[58:59]
	global_load_dwordx4 v[232:235], v[188:189], off
	s_nop 0
	global_load_dwordx4 v[236:239], v[188:189], off offset:16
	v_lshl_add_u64 v[248:249], v[172:173], 0, v[178:179]
	global_load_dwordx4 v[240:243], v[248:249], off
	s_nop 0
	global_load_dwordx4 v[244:247], v[248:249], off offset:16
	s_waitcnt vmcnt(7)
	v_pk_mul_f32 v[208:209], v[20:21], v[132:133]
	v_pk_mul_f32 v[210:211], v[18:19], v[130:131]
	s_waitcnt vmcnt(6)
	v_pk_mul_f32 v[212:213], v[12:13], v[136:137]
	v_pk_mul_f32 v[224:225], v[10:11], v[134:135]
	v_pk_mul_f32 v[132:133], v[40:41], v[132:133]
	v_pk_mul_f32 v[130:131], v[38:39], v[130:131]
	v_pk_mul_f32 v[136:137], v[32:33], v[136:137]
	v_pk_mul_f32 v[134:135], v[30:31], v[134:135]
	s_waitcnt vmcnt(5)
	v_pk_fma_f32 v[208:209], v[40:41], v[140:141], v[208:209] neg_lo:[0,0,1] neg_hi:[0,0,1]
	v_pk_fma_f32 v[210:211], v[38:39], v[138:139], v[210:211] neg_lo:[0,0,1] neg_hi:[0,0,1]
	s_waitcnt vmcnt(4)
	v_pk_fma_f32 v[212:213], v[32:33], v[144:145], v[212:213] neg_lo:[0,0,1] neg_hi:[0,0,1]
	v_pk_fma_f32 v[224:225], v[30:31], v[142:143], v[224:225] neg_lo:[0,0,1] neg_hi:[0,0,1]
	v_pk_fma_f32 v[132:133], v[20:21], v[140:141], v[132:133]
	v_pk_fma_f32 v[130:131], v[18:19], v[138:139], v[130:131]
	v_pk_fma_f32 v[136:137], v[12:13], v[144:145], v[136:137]
	v_pk_fma_f32 v[134:135], v[10:11], v[142:143], v[134:135]
	v_pk_mul_f32 v[138:139], v[190:191], v[208:209] op_sel_hi:[0,1]
	v_pk_mul_f32 v[140:141], v[190:191], v[210:211] op_sel_hi:[0,1]
	v_pk_mul_f32 v[142:143], v[190:191], v[212:213] op_sel_hi:[0,1]
	v_pk_mul_f32 v[144:145], v[190:191], v[224:225] op_sel_hi:[0,1]
	v_pk_mul_f32 v[208:209], v[190:191], v[132:133] op_sel_hi:[0,1]
	v_pk_mul_f32 v[210:211], v[190:191], v[130:131] op_sel_hi:[0,1]
	v_pk_mul_f32 v[212:213], v[190:191], v[136:137] op_sel_hi:[0,1]
	v_pk_mul_f32 v[136:137], v[190:191], v[134:135] op_sel_hi:[0,1]
	v_cvt_pk_bf16_f32 v130, v140, v141
	v_cvt_pk_bf16_f32 v131, v138, v139
	v_cvt_pk_bf16_f32 v132, v144, v145
	v_cvt_pk_bf16_f32 v133, v142, v143
	v_cvt_pk_bf16_f32 v134, v210, v211
	v_cvt_pk_bf16_f32 v135, v208, v209
	v_cvt_pk_bf16_f32 v136, v136, v137
	v_cvt_pk_bf16_f32 v137, v212, v213
	global_store_dwordx4 v[194:195], v[130:133], off
	global_store_dwordx4 v[206:207], v[134:137], off
	v_mul_f32_e32 v172, v168, v222
	s_waitcnt vmcnt(3)
	v_pk_mul_f32 v[188:189], v[8:9], v[234:235]
	v_pk_mul_f32 v[194:195], v[6:7], v[232:233]
	s_waitcnt vmcnt(2)
	v_pk_mul_f32 v[206:207], v[4:5], v[238:239]
	v_pk_mul_f32 v[208:209], v[2:3], v[236:237]
	v_pk_mul_f32 v[234:235], v[24:25], v[234:235]
	v_pk_mul_f32 v[232:233], v[22:23], v[232:233]
	v_pk_mul_f32 v[238:239], v[16:17], v[238:239]
	v_pk_mul_f32 v[236:237], v[14:15], v[236:237]
	s_waitcnt vmcnt(1)
	v_pk_fma_f32 v[188:189], v[24:25], v[242:243], v[188:189] neg_lo:[0,0,1] neg_hi:[0,0,1]
	v_pk_fma_f32 v[194:195], v[22:23], v[240:241], v[194:195] neg_lo:[0,0,1] neg_hi:[0,0,1]
	s_waitcnt vmcnt(0)
	v_pk_fma_f32 v[206:207], v[16:17], v[246:247], v[206:207] neg_lo:[0,0,1] neg_hi:[0,0,1]
	v_pk_fma_f32 v[208:209], v[14:15], v[244:245], v[208:209] neg_lo:[0,0,1] neg_hi:[0,0,1]
	v_pk_fma_f32 v[234:235], v[8:9], v[242:243], v[234:235]
	v_pk_fma_f32 v[232:233], v[6:7], v[240:241], v[232:233]
	v_pk_fma_f32 v[238:239], v[4:5], v[246:247], v[238:239]
	v_pk_fma_f32 v[236:237], v[2:3], v[244:245], v[236:237]
	v_pk_mul_f32 v[240:241], v[172:173], v[188:189] op_sel_hi:[0,1]
	v_pk_mul_f32 v[242:243], v[172:173], v[194:195] op_sel_hi:[0,1]
	v_pk_mul_f32 v[244:245], v[172:173], v[206:207] op_sel_hi:[0,1]
	v_pk_mul_f32 v[246:247], v[172:173], v[208:209] op_sel_hi:[0,1]
	v_pk_mul_f32 v[188:189], v[172:173], v[234:235] op_sel_hi:[0,1]
	v_pk_mul_f32 v[194:195], v[172:173], v[232:233] op_sel_hi:[0,1]
	v_pk_mul_f32 v[206:207], v[172:173], v[238:239] op_sel_hi:[0,1]
	v_pk_mul_f32 v[238:239], v[172:173], v[236:237] op_sel_hi:[0,1]
	v_cvt_pk_bf16_f32 v232, v242, v243
	v_cvt_pk_bf16_f32 v233, v240, v241
	v_cvt_pk_bf16_f32 v234, v246, v247
	v_cvt_pk_bf16_f32 v235, v244, v245
	v_cvt_pk_bf16_f32 v236, v194, v195
	v_cvt_pk_bf16_f32 v237, v188, v189
	v_cvt_pk_bf16_f32 v238, v238, v239
	v_cvt_pk_bf16_f32 v239, v206, v207
	global_store_dwordx4 v[174:175], v[232:235], off
	global_store_dwordx4 v[176:177], v[236:239], off
	s_branch .LBB0_289
